# attention work order: items walked two heads at a time (long items first) to shorten the phase tail
# speedup vs baseline: 1.0070x; 1.0016x over previous
.LBB0_835:
	s_or_b64 exec, exec, s[0:1]
	s_add_i32 s0, 0, 0x10000
	s_cmp_lg_u32 s0, -1
	s_cselect_b32 s0, s0, 0
	s_cselect_b32 s1, s13, 0
	v_mov_b32_e32 v0, s0
	v_mov_b32_e32 v1, s1
	s_waitcnt lgkmcnt(0)
	s_barrier
	flat_load_dword v7, v[0:1] sc0 sc1
	s_waitcnt vmcnt(0) lgkmcnt(0)
	s_barrier
	v_cmp_gt_i32_e32 vcc, s52, v7
	s_and_saveexec_b64 s[0:1], vcc
	s_xor_b64 s[42:43], exec, s[0:1]
	s_cbranch_execz .LBB0_861
	v_cmp_lt_i32_e32 vcc, 7, v7
	s_and_saveexec_b64 s[0:1], vcc
	s_xor_b64 s[0:1], exec, s[0:1]
	s_cbranch_execz .LBB0_838
	v_add_u32_e32 v0, -8, v7
	v_lshrrev_b32_e32 v4, 7, v0
	v_and_b32_e32 v1, 1, v0
	v_lshl_or_b32 v4, v4, 1, v1
	v_bfe_u32 v0, v0, 1, 6
	v_sub_u32_e32 v137, 64, v0
	v_lshlrev_b32_e32 v1, 12, v134
	v_lshlrev_b32_e32 v0, 6, v0
	v_lshlrev_b32_e32 v112, 23, v134
	v_bitop3_b32 v6, v0, s53, v1 bitop3:0x36
	v_lshl_add_u64 v[0:1], s[20:21], 0, v[112:113]
	v_lshlrev_b32_e32 v2, 8, v4
	v_mov_b32_e32 v3, v113
	v_lshl_add_u64 v[0:1], v[0:1], 0, v[2:3]
	v_lshl_add_u32 v2, v134, 3, v4
	v_lshlrev_b32_e32 v112, 7, v4
	v_lshlrev_b64 v[2:3], 20, v[2:3]
	v_lshlrev_b32_e32 v171, 6, v137
	v_lshl_add_u64 v[2:3], s[22:23], 0, v[2:3]
	v_mov_b32_e32 v135, v112
	v_mov_b64_e32 v[138:139], v[112:113]
